# P0: nt (streaming) cache policy on the once-read f32 x row loads so they do not displace the bf16 copies the next phase reads
# speedup vs baseline: 1.0202x; 1.0118x over previous
; #define LAS __attribute__((address_space(3)))
; __global__ void __launch_bounds__(NTHR, 2) hybrid_fwd(Args args) {
;     ...
;         __syncthreads();
;         LAS float* gwt = (LAS float*)ldsl;
; #pragma unroll
;         for (int i = 0; i < 16; ++i) { const int idx = tid + i * NTHR, h = idx & 7, k = idx >> 3; gwt[h * 1024 + k] = norm_mix_g[k] * w_in[(size_t)k * INC + 2048 + h]; }
.LBB0_191:
	s_and_b32 s71, s72, 0xffffffc0
	v_add_u32_e32 v33, s71, v32
	v_ashrrev_i32_e32 v2, 3, v33
	v_ashrrev_i32_e32 v3, 31, v2
	v_lshl_add_u64 v[4:5], v[2:3], 2, s[6:7]
	s_barrier
	v_and_b32_e32 v1, 7, v32
	global_load_dword v3, v[4:5], off
	s_movk_i32 s3, 0x4020
	v_mov_b64_e32 v[4:5], s[10:11]
	v_mad_i64_i32 v[6:7], s[4:5], v2, s3, v[4:5]
	v_lshlrev_b32_e32 v34, 2, v1
	v_mov_b32_e32 v35, 0
	v_lshl_add_u64 v[6:7], v[6:7], 0, v[34:35]
	s_movk_i32 s4, 0x2000
	v_add_co_u32_e32 v6, vcc, s4, v6
	v_and_b32_e32 v174, 64, v212
	s_nop 0
	v_addc_co_u32_e32 v7, vcc, 0, v7, vcc
	global_load_dword v42, v[6:7], off
	v_add_u32_e32 v6, 0x200, v33
	v_ashrrev_i32_e32 v6, 3, v6
	v_ashrrev_i32_e32 v7, 31, v6
	v_lshl_add_u64 v[8:9], v[6:7], 2, s[6:7]
	global_load_dword v7, v[8:9], off
	v_mad_i64_i32 v[8:9], s[10:11], v6, s3, v[4:5]
	v_lshl_add_u64 v[8:9], v[8:9], 0, v[34:35]
	v_add_co_u32_e32 v8, vcc, s4, v8
	s_mov_b32 s35, 0
	s_nop 0
	v_addc_co_u32_e32 v9, vcc, 0, v9, vcc
	global_load_dword v43, v[8:9], off
	v_add_u32_e32 v8, 0x400, v33
	v_ashrrev_i32_e32 v8, 3, v8
	v_ashrrev_i32_e32 v9, 31, v8
	v_lshl_add_u64 v[10:11], v[8:9], 2, s[6:7]
	global_load_dword v9, v[10:11], off
	v_mad_i64_i32 v[10:11], s[10:11], v8, s3, v[4:5]
	v_lshl_add_u64 v[10:11], v[10:11], 0, v[34:35]
	v_add_co_u32_e32 v10, vcc, s4, v10
	s_cmp_lt_i32 s26, 0x8000
	s_nop 0
	v_addc_co_u32_e32 v11, vcc, 0, v11, vcc
	global_load_dword v44, v[10:11], off
	v_add_u32_e32 v10, 0x600, v33
	v_ashrrev_i32_e32 v10, 3, v10
	v_ashrrev_i32_e32 v11, 31, v10
	v_lshl_add_u64 v[12:13], v[10:11], 2, s[6:7]
	global_load_dword v11, v[12:13], off
	v_mad_i64_i32 v[12:13], s[10:11], v10, s3, v[4:5]
	v_lshl_add_u64 v[12:13], v[12:13], 0, v[34:35]
	v_add_co_u32_e32 v12, vcc, s4, v12
	s_waitcnt vmcnt(5)
	v_mul_f32_e32 v3, v3, v42
	v_addc_co_u32_e32 v13, vcc, 0, v13, vcc
	global_load_dword v45, v[12:13], off
	v_add_u32_e32 v12, 0x800, v33
	v_ashrrev_i32_e32 v12, 3, v12
	v_ashrrev_i32_e32 v13, 31, v12
	v_lshl_add_u64 v[14:15], v[12:13], 2, s[6:7]
	global_load_dword v13, v[14:15], off
	v_mad_i64_i32 v[14:15], s[10:11], v12, s3, v[4:5]
	v_lshl_add_u64 v[14:15], v[14:15], 0, v[34:35]
	v_add_co_u32_e32 v14, vcc, s4, v14
	s_nop 1
	v_addc_co_u32_e32 v15, vcc, 0, v15, vcc
	global_load_dword v46, v[14:15], off
	v_add_u32_e32 v14, 0xa00, v33
	v_ashrrev_i32_e32 v14, 3, v14
	v_ashrrev_i32_e32 v15, 31, v14
	v_lshl_add_u64 v[16:17], v[14:15], 2, s[6:7]
	global_load_dword v15, v[16:17], off
	v_mad_i64_i32 v[16:17], s[10:11], v14, s3, v[4:5]
	v_lshl_add_u64 v[16:17], v[16:17], 0, v[34:35]
	v_add_co_u32_e32 v16, vcc, s4, v16
	s_nop 1
	v_addc_co_u32_e32 v17, vcc, 0, v17, vcc
	global_load_dword v47, v[16:17], off
	v_add_u32_e32 v16, 0xc00, v33
	v_ashrrev_i32_e32 v16, 3, v16
	v_ashrrev_i32_e32 v17, 31, v16
	v_lshl_add_u64 v[18:19], v[16:17], 2, s[6:7]
	global_load_dword v17, v[18:19], off
	v_mad_i64_i32 v[18:19], s[10:11], v16, s3, v[4:5]
	v_lshl_add_u64 v[18:19], v[18:19], 0, v[34:35]
	v_add_co_u32_e32 v18, vcc, s4, v18
	s_nop 1
	v_addc_co_u32_e32 v19, vcc, 0, v19, vcc
	global_load_dword v48, v[18:19], off
	v_add_u32_e32 v18, 0xe00, v33
	v_ashrrev_i32_e32 v18, 3, v18
	v_ashrrev_i32_e32 v19, 31, v18
	v_lshl_add_u64 v[20:21], v[18:19], 2, s[6:7]
	global_load_dword v19, v[20:21], off
	v_mad_i64_i32 v[20:21], s[10:11], v18, s3, v[4:5]
	v_lshl_add_u64 v[20:21], v[20:21], 0, v[34:35]
	v_add_co_u32_e32 v20, vcc, s4, v20
	s_nop 1
	v_addc_co_u32_e32 v21, vcc, 0, v21, vcc
	global_load_dword v49, v[20:21], off
	v_add_u32_e32 v20, 0x1000, v33
	v_ashrrev_i32_e32 v20, 3, v20
	v_ashrrev_i32_e32 v21, 31, v20
	v_lshl_add_u64 v[22:23], v[20:21], 2, s[6:7]
	global_load_dword v21, v[22:23], off
	v_mad_i64_i32 v[22:23], s[10:11], v20, s3, v[4:5]
	v_lshl_add_u64 v[22:23], v[22:23], 0, v[34:35]
	v_add_co_u32_e32 v22, vcc, s4, v22
	s_nop 1
	v_addc_co_u32_e32 v23, vcc, 0, v23, vcc
	global_load_dword v50, v[22:23], off
	v_add_u32_e32 v22, 0x1200, v33
	v_ashrrev_i32_e32 v22, 3, v22
	v_ashrrev_i32_e32 v23, 31, v22
	v_lshl_add_u64 v[24:25], v[22:23], 2, s[6:7]
	global_load_dword v23, v[24:25], off
	v_mad_i64_i32 v[24:25], s[10:11], v22, s3, v[4:5]
	v_lshl_add_u64 v[24:25], v[24:25], 0, v[34:35]
	v_add_co_u32_e32 v24, vcc, s4, v24
	s_nop 1
	v_addc_co_u32_e32 v25, vcc, 0, v25, vcc
	global_load_dword v51, v[24:25], off
	v_add_u32_e32 v24, 0x1400, v33
	v_ashrrev_i32_e32 v24, 3, v24
	v_ashrrev_i32_e32 v25, 31, v24
	v_lshl_add_u64 v[26:27], v[24:25], 2, s[6:7]
	global_load_dword v25, v[26:27], off
	v_mad_i64_i32 v[26:27], s[10:11], v24, s3, v[4:5]
	v_lshl_add_u64 v[26:27], v[26:27], 0, v[34:35]
	v_add_co_u32_e32 v26, vcc, s4, v26
	s_nop 1
	v_addc_co_u32_e32 v27, vcc, 0, v27, vcc
	global_load_dword v52, v[26:27], off
	v_add_u32_e32 v26, 0x1600, v33
	v_ashrrev_i32_e32 v26, 3, v26
	v_ashrrev_i32_e32 v27, 31, v26
	v_lshl_add_u64 v[28:29], v[26:27], 2, s[6:7]
	global_load_dword v27, v[28:29], off
	v_mad_i64_i32 v[28:29], s[10:11], v26, s3, v[4:5]
	v_lshl_add_u64 v[28:29], v[28:29], 0, v[34:35]
	v_add_co_u32_e32 v28, vcc, s4, v28
	s_nop 1
	v_addc_co_u32_e32 v29, vcc, 0, v29, vcc
	global_load_dword v53, v[28:29], off
	v_add_u32_e32 v28, 0x1800, v33
	v_ashrrev_i32_e32 v28, 3, v28
	v_ashrrev_i32_e32 v29, 31, v28
	v_lshl_add_u64 v[30:31], v[28:29], 2, s[6:7]
	global_load_dword v29, v[30:31], off
	v_mad_i64_i32 v[30:31], s[10:11], v28, s3, v[4:5]
	v_lshl_add_u64 v[30:31], v[30:31], 0, v[34:35]
	v_add_co_u32_e32 v30, vcc, s4, v30
	s_nop 1
	v_addc_co_u32_e32 v31, vcc, 0, v31, vcc
	global_load_dword v54, v[30:31], off
	v_add_u32_e32 v30, 0x1a00, v33
	v_ashrrev_i32_e32 v30, 3, v30
	v_ashrrev_i32_e32 v31, 31, v30
	v_lshl_add_u64 v[36:37], v[30:31], 2, s[6:7]
	global_load_dword v31, v[36:37], off
	v_mad_i64_i32 v[36:37], s[10:11], v30, s3, v[4:5]
	v_lshl_add_u64 v[36:37], v[36:37], 0, v[34:35]
	v_add_co_u32_e32 v36, vcc, s4, v36
	s_nop 1
	v_addc_co_u32_e32 v37, vcc, 0, v37, vcc
	global_load_dword v55, v[36:37], off
	v_add_u32_e32 v36, 0x1c00, v33
	v_ashrrev_i32_e32 v36, 3, v36
	v_ashrrev_i32_e32 v37, 31, v36
	v_lshl_add_u64 v[38:39], v[36:37], 2, s[6:7]
	global_load_dword v37, v[38:39], off
	v_mad_i64_i32 v[38:39], s[10:11], v36, s3, v[4:5]
	v_lshl_add_u64 v[38:39], v[38:39], 0, v[34:35]
	v_add_co_u32_e32 v38, vcc, s4, v38
	v_add_u32_e32 v33, 0x1e00, v33
	s_nop 0
	v_addc_co_u32_e32 v39, vcc, 0, v39, vcc
	global_load_dword v56, v[38:39], off
	v_ashrrev_i32_e32 v38, 3, v33
	v_ashrrev_i32_e32 v39, 31, v38
	v_lshl_add_u64 v[40:41], v[38:39], 2, s[6:7]
	v_mad_i64_i32 v[4:5], s[6:7], v38, s3, v[4:5]
	v_lshl_add_u64 v[4:5], v[4:5], 0, v[34:35]
	v_add_co_u32_e32 v4, vcc, s4, v4
	global_load_dword v33, v[40:41], off
	s_nop 0
	v_addc_co_u32_e32 v5, vcc, 0, v5, vcc
	global_load_dword v4, v[4:5], off
	v_lshl_add_u32 v5, v1, 12, 0
	v_lshl_add_u32 v2, v2, 2, v5
	ds_write_b32 v2, v3
	s_waitcnt vmcnt(28)
; __global__ void __launch_bounds__(NTHR, 2) hybrid_fwd(Args args) {
;     ...
;         for (int i = 0; i < 16; ++i) { const int idx = tid + i * NTHR, h = idx & 7, k = idx >> 3; gwt[h * 1024 + k] = norm_mix_g[k] * w_in[(size_t)k * INC + 2048 + h]; }
;         __syncthreads();
;         const int rpb = (T + G - 1) / G, rpw = (rpb + NWAVES - 1) / NWAVES;
;         for (int rr_ = 0; rr_ < REP_P0R; ++rr_)
;         {
;             (void)rpw;
;             f32x4 v[4], nx[4];
;             if (gw < T) {
; #pragma unroll
;                 for (int j = 0; j < 4; ++j) nx[j] = ((const f32x4*)(x + (size_t)gw * DM) + lane)[64 * j]; }
	v_mul_f32_e32 v2, v7, v43
	v_lshl_add_u32 v3, v6, 2, v5
	ds_write_b32 v3, v2
	s_waitcnt vmcnt(26)
	v_mul_f32_e32 v2, v9, v44
	v_lshl_add_u32 v3, v8, 2, v5
	ds_write_b32 v3, v2
	s_waitcnt vmcnt(24)
	v_mul_f32_e32 v2, v11, v45
	v_lshl_add_u32 v3, v10, 2, v5
	ds_write_b32 v3, v2
	s_waitcnt vmcnt(22)
	v_mul_f32_e32 v2, v13, v46
	v_lshl_add_u32 v3, v12, 2, v5
	ds_write_b32 v3, v2
	s_waitcnt vmcnt(20)
	v_mul_f32_e32 v2, v15, v47
	v_lshl_add_u32 v3, v14, 2, v5
	ds_write_b32 v3, v2
	s_waitcnt vmcnt(18)
	v_mul_f32_e32 v2, v17, v48
	v_lshl_add_u32 v3, v16, 2, v5
	ds_write_b32 v3, v2
	s_waitcnt vmcnt(16)
	v_mul_f32_e32 v2, v19, v49
	v_lshl_add_u32 v3, v18, 2, v5
	ds_write_b32 v3, v2
	s_waitcnt vmcnt(14)
	v_mul_f32_e32 v2, v21, v50
	v_lshl_add_u32 v3, v20, 2, v5
	ds_write_b32 v3, v2
	s_waitcnt vmcnt(12)
	v_mul_f32_e32 v2, v23, v51
	v_lshl_add_u32 v3, v22, 2, v5
	ds_write_b32 v3, v2
	s_waitcnt vmcnt(10)
	v_mul_f32_e32 v2, v25, v52
	v_lshl_add_u32 v3, v24, 2, v5
	ds_write_b32 v3, v2
	s_waitcnt vmcnt(8)
	v_mul_f32_e32 v2, v27, v53
	v_lshl_add_u32 v3, v26, 2, v5
	ds_write_b32 v3, v2
	v_lshl_add_u32 v3, v28, 2, v5
	v_cmp_eq_u32_e64 s[4:5], 0, v32
	s_waitcnt vmcnt(6)
	v_mul_f32_e32 v2, v29, v54
	ds_write_b32 v3, v2
	v_lshl_add_u32 v3, v30, 2, v5
	s_waitcnt vmcnt(4)
	v_mul_f32_e32 v2, v31, v55
	ds_write_b32 v3, v2
	v_lshl_add_u32 v3, v36, 2, v5
	s_waitcnt vmcnt(2)
	v_mul_f32_e32 v2, v37, v56
	ds_write_b32 v3, v2
	v_lshl_add_u32 v3, v38, 2, v5
	s_waitcnt vmcnt(0)
	v_mul_f32_e32 v2, v33, v4
	ds_write_b32 v3, v2
	v_add_u32_e32 v2, 64, v174
	v_xor_b32_e32 v3, 1, v212
	v_cmp_lt_i32_e32 vcc, v3, v2
	v_ashrrev_i32_e32 v33, 31, v32
	s_waitcnt lgkmcnt(0)
	v_cndmask_b32_e32 v3, v212, v3, vcc
	v_lshlrev_b32_e32 v218, 2, v3
	v_xor_b32_e32 v3, 2, v212
	v_cmp_lt_i32_e32 vcc, v3, v2
	s_barrier
	s_nop 0
	v_cndmask_b32_e32 v3, v212, v3, vcc
	v_lshlrev_b32_e32 v219, 2, v3
	v_xor_b32_e32 v3, 4, v212
	v_cmp_lt_i32_e32 vcc, v3, v2
	s_nop 1
	v_cndmask_b32_e32 v3, v212, v3, vcc
	v_lshlrev_b32_e32 v34, 2, v3
	v_xor_b32_e32 v3, 8, v212
	v_cmp_lt_i32_e32 vcc, v3, v2
	s_nop 1
	v_cndmask_b32_e32 v3, v212, v3, vcc
	v_lshlrev_b32_e32 v50, 2, v3
	v_xor_b32_e32 v3, 16, v212
	v_cmp_lt_i32_e32 vcc, v3, v2
	s_nop 1
	v_cndmask_b32_e32 v3, v212, v3, vcc
	v_lshlrev_b32_e32 v213, 2, v3
	v_xor_b32_e32 v3, 32, v212
	v_cmp_lt_i32_e32 vcc, v3, v2
	s_nop 1
	v_cndmask_b32_e32 v2, v212, v3, vcc
	v_lshlrev_b32_e32 v220, 2, v2
	s_cbranch_scc0 .LBB0_200
	s_ashr_i32 s27, s26, 31
	s_lshl_b64 s[6:7], s[26:27], 12
	s_add_u32 s6, s8, s6
	v_lshlrev_b64 v[2:3], 4, v[32:33]
	s_addc_u32 s7, s9, s7
	v_lshl_add_u64 v[4:5], s[6:7], 0, v[2:3]
	global_load_dwordx4 v[28:31], v[4:5], off nt
	global_load_dwordx4 v[24:27], v[4:5], off offset:1024 nt
	global_load_dwordx4 v[20:23], v[4:5], off offset:2048 nt
	global_load_dwordx4 v[16:19], v[4:5], off offset:3072 nt
	v_cmp_eq_u32_e64 s[6:7], 0, v1
	v_ashrrev_i32_e32 v1, 31, v0
	v_lshl_add_u64 v[40:41], v[0:1], 2, s[14:15]
	s_lshl_b64 s[14:15], s[26:27], 2
	v_lshlrev_b64 v[0:1], 13, v[0:1]
	s_add_u32 s54, s14, 0x3400000
	v_lshlrev_b32_e32 v4, 4, v32
	v_and_b32_e32 v5, 32, v32
	v_and_b32_e32 v6, 16, v32
	v_and_b32_e32 v7, 8, v32
	s_mov_b64 s[36:37], 0x3200000
	v_lshl_add_u64 v[0:1], s[24:25], 0, v[0:1]
	s_addc_u32 s55, s15, 0
	s_ashr_i32 s29, s28, 31
	s_lshl_b64 s[14:15], s[26:27], 11
	s_mov_b32 s3, 0x3c00000
	v_mov_b32_e32 v51, 0x358637bd
	s_mov_b32 s21, 0xf800000
	v_mov_b32_e32 v52, 0x260
	s_mov_b32 s46, 0xbfb8aa3b
	s_mov_b32 s47, 0xb2a5705f
	s_mov_b32 s48, 0x42ce8ed0
	s_mov_b32 s49, 0xc2b17218
	s_mov_b32 s50, 0x7f800000
	s_mov_b32 s51, 0x3f2aaaab
	v_mov_b32_e32 v53, 0x3ecc95a3
	s_mov_b32 s52, 0x3f317218
	s_mov_b32 s53, 0x33800000
	v_mov_b32_e32 v54, 0x7f800000
	v_mov_b32_e32 v36, 0x3f317218
	s_mov_b32 s34, s26
	v_lshl_add_u64 v[38:39], s[8:9], 0, v[2:3]
	v_cmp_eq_u32_e64 s[8:9], 0, v5
	v_cmp_eq_u32_e64 s[10:11], 0, v6
	v_cmp_eq_u32_e64 s[12:13], 0, v7
	v_add_u32_e32 v55, 0, v4
	v_lshl_add_u64 v[42:43], v[0:1], 0, s[36:37]
	s_lshl_b64 s[36:37], s[28:29], 2
	v_lshl_add_u64 v[44:45], v[32:33], 3, s[14:15]
	s_lshl_b64 s[38:39], s[28:29], 11
	s_waitcnt vmcnt(3)
	v_mov_b32_e32 v0, v28
	v_mov_b32_e32 v1, v29
	v_mov_b32_e32 v2, v30
	v_mov_b32_e32 v3, v31
	s_waitcnt vmcnt(2)
	v_mov_b32_e32 v4, v24
	v_mov_b32_e32 v5, v25
	v_mov_b32_e32 v6, v26
	v_mov_b32_e32 v7, v27
	s_waitcnt vmcnt(1)
	v_mov_b32_e32 v8, v20
	v_mov_b32_e32 v9, v21
	v_mov_b32_e32 v10, v22
	v_mov_b32_e32 v11, v23
	s_waitcnt vmcnt(0)
	v_mov_b32_e32 v12, v16
	v_mov_b32_e32 v13, v17
	v_mov_b32_e32 v14, v18
	v_mov_b32_e32 v15, v19
	s_branch .LBB0_194

; __global__ void __launch_bounds__(NTHR, 2) hybrid_fwd(Args args) {
;     ...
;             for (int row = gw; row < T; row += NGW) {
; #pragma unroll
;                 for (int j = 0; j < 4; ++j) v[j] = nx[j];
;                 if (row + NGW < T) {
; #pragma unroll
;                     for (int j = 0; j < 4; ++j) nx[j] = ((const f32x4*)(x + (size_t)(row + NGW) * DM) + lane)[64 * j]; }
.LBB0_194:
	s_add_i32 s40, s34, s28
	s_cmpk_gt_i32 s40, 0x7fff
	s_cselect_b64 s[42:43], -1, 0
	s_and_b64 vcc, exec, s[42:43]
	s_cbranch_vccnz .LBB0_196
	s_ashr_i32 s41, s40, 31
	s_lshl_b64 s[14:15], s[40:41], 12
	v_lshl_add_u64 v[12:13], v[38:39], 0, s[14:15]
	global_load_dwordx4 v[0:3], v[12:13], off nt
	global_load_dwordx4 v[4:7], v[12:13], off offset:1024 nt
	global_load_dwordx4 v[8:11], v[12:13], off offset:2048 nt
	s_nop 0
	global_load_dwordx4 v[12:15], v[12:13], off offset:3072 nt
